# v17 + prep-phase serial max-abs scans (8 loops, one 8-byte load per trip) rewritten as 16-floats-per-trip folds with 4 dwordx4 loads in flight
# speedup vs baseline: 1.0049x; 1.0036x over previous
; __device__ __forceinline__ float absmax_n(const float* w, int n) { float m = 0.f; for (int i = 0; i < n; ++i) m = fmaxf(m, fabsf(w[i])); return m; }
; __global__ void __launch_bounds__(512, 2) mega_fwd(Args args) {
;     ...
;                 for (int i = 0; i < 64; ++i) { s1 += args.in[20][l * 64 + i] * args.in[21][l * 64 + i]; s2 += args.in[22][l * 64 + i] * args.in[23][l * 64 + i]; }
;                 const float lam_init = 0.8f - 0.6f * expf(-0.3f * (float)l);
;                 LAM[l * 4 + 0] = expf(s1) - expf(s2) + lam_init;
;                 const float mAq = absmax_n(args.in[9] + l * 128, 128), mAk = absmax_n(args.in[10] + l * 128, 128);
.LBB0_761:
	v_lshl_add_u64 v[28:29], v[4:5], 0, s[14:15]
	v_lshl_add_u64 v[36:37], v[6:7], 0, s[14:15]
	v_lshl_add_u64 v[32:33], v[10:11], 0, s[14:15]
	v_lshl_add_u64 v[40:41], v[8:9], 0, s[14:15]
	global_load_dwordx4 v[12:15], v[28:29], off
	global_load_dwordx4 v[16:19], v[32:33], off
	global_load_dwordx4 v[20:23], v[36:37], off
	global_load_dwordx4 v[24:27], v[40:41], off
	s_nop 0
	global_load_dwordx4 v[28:31], v[28:29], off offset:16
	s_nop 0
	global_load_dwordx4 v[32:35], v[32:33], off offset:16
	s_nop 0
	global_load_dwordx4 v[36:39], v[36:37], off offset:16
	s_nop 0
	global_load_dwordx4 v[40:43], v[40:41], off offset:16
	s_add_u32 s14, s14, 32
	s_addc_u32 s15, s15, 0
	s_cmpk_eq_i32 s14, 0x100
	s_waitcnt vmcnt(7)
	v_mov_b32_e32 v44, v12
	s_waitcnt vmcnt(6)
	v_mov_b32_e32 v45, v16
	s_waitcnt vmcnt(5)
	v_mov_b32_e32 v46, v20
	s_waitcnt vmcnt(4)
	v_mov_b32_e32 v47, v24
	v_mov_b32_e32 v16, v13
	v_mov_b32_e32 v24, v21
	v_pk_fma_f32 v[0:1], v[44:45], v[46:47], v[0:1]
	v_mov_b32_e32 v12, v14
	v_mov_b32_e32 v13, v18
	v_mov_b32_e32 v20, v22
	v_mov_b32_e32 v21, v26
	v_pk_fma_f32 v[0:1], v[16:17], v[24:25], v[0:1]
	v_mov_b32_e32 v18, v15
	v_mov_b32_e32 v26, v23
	v_pk_fma_f32 v[0:1], v[12:13], v[20:21], v[0:1]
	s_waitcnt vmcnt(3)
	v_mov_b32_e32 v14, v28
	s_waitcnt vmcnt(2)
	v_mov_b32_e32 v15, v32
	s_waitcnt vmcnt(1)
	v_mov_b32_e32 v22, v36
	s_waitcnt vmcnt(0)
	v_mov_b32_e32 v23, v40
	v_pk_fma_f32 v[0:1], v[18:19], v[26:27], v[0:1]
	v_mov_b32_e32 v32, v29
	v_mov_b32_e32 v40, v37
	v_pk_fma_f32 v[0:1], v[14:15], v[22:23], v[0:1]
	v_mov_b32_e32 v28, v30
	v_mov_b32_e32 v29, v34
	v_mov_b32_e32 v36, v38
	v_mov_b32_e32 v37, v42
	v_pk_fma_f32 v[0:1], v[32:33], v[40:41], v[0:1]
	v_mov_b32_e32 v34, v31
	v_mov_b32_e32 v42, v39
	v_pk_fma_f32 v[0:1], v[28:29], v[36:37], v[0:1]
	s_nop 0
	v_pk_fma_f32 v[0:1], v[34:35], v[42:43], v[0:1]
	s_cbranch_scc0 .LBB0_761
	v_cvt_f32_i32_e32 v4, v186
	s_mov_b32 s4, 0x3fb8aa3b
	s_mov_b32 s2, 0xc2ce8ed0
	s_mov_b32 s3, 0x42b17218
	v_mul_f32_e32 v4, 0xbe99999a, v4
	v_mul_f32_e32 v5, 0x3fb8aa3b, v4
	v_fma_f32 v6, v4, s4, -v5
	v_rndne_f32_e32 v7, v5
	v_fmac_f32_e32 v6, 0x32a5705f, v4
	v_sub_f32_e32 v5, v5, v7
	v_add_f32_e32 v5, v5, v6
	v_cvt_i32_f32_e32 v7, v7
	v_exp_f32_e32 v5, v5
	v_mul_f32_e32 v6, 0x3fb8aa3b, v0
	v_cmp_ngt_f32_e32 vcc, s2, v4
	v_lshlrev_b32_e32 v10, 7, v186
	v_ldexp_f32 v5, v5, v7
	v_rndne_f32_e32 v7, v6
	v_sub_f32_e32 v8, v6, v7
	v_fma_f32 v6, v0, s4, -v6
	v_fmac_f32_e32 v6, 0x32a5705f, v0
	v_add_f32_e32 v6, v8, v6
	v_exp_f32_e32 v6, v6
	v_cvt_i32_f32_e32 v7, v7
	v_cndmask_b32_e32 v5, 0, v5, vcc
	v_cmp_nlt_f32_e32 vcc, s3, v4
	v_readlane_b32 s56, v253, 32
	v_ashrrev_i32_e32 v11, 31, v10
	v_cndmask_b32_e32 v4, v229, v5, vcc
	v_ldexp_f32 v5, v6, v7
	v_mul_f32_e32 v6, 0x3fb8aa3b, v1
	v_rndne_f32_e32 v7, v6
	v_sub_f32_e32 v8, v6, v7
	v_fma_f32 v6, v1, s4, -v6
	v_fmac_f32_e32 v6, 0x32a5705f, v1
	v_add_f32_e32 v6, v8, v6
	v_exp_f32_e32 v6, v6
	v_cvt_i32_f32_e32 v7, v7
	v_cmp_ngt_f32_e32 vcc, s2, v0
	v_fmamk_f32 v4, v4, 0xbf19999a, v250
	v_readlane_b32 s58, v253, 34
	v_cndmask_b32_e32 v5, 0, v5, vcc
	v_cmp_nlt_f32_e32 vcc, s3, v0
	v_readlane_b32 s59, v253, 35
	v_mov_b32_e32 v14, 0
	v_cndmask_b32_e32 v0, v229, v5, vcc
	v_ldexp_f32 v5, v6, v7
	v_cmp_ngt_f32_e32 vcc, s2, v1
	v_lshl_add_u64 v[8:9], v[10:11], 2, s[58:59]
	s_mov_b64 s[26:27], 0
	v_cndmask_b32_e32 v5, 0, v5, vcc
	v_cmp_nlt_f32_e32 vcc, s3, v1
	v_readlane_b32 s2, v251, 14
	v_readlane_b32 s3, v251, 15
	v_cndmask_b32_e32 v1, v229, v5, vcc
	v_sub_f32_e32 v0, v0, v1
	v_add_f32_e32 v6, v4, v0
	v_lshlrev_b32_e32 v0, 2, v186
	v_ashrrev_i32_e32 v1, 31, v0
	v_lshl_add_u64 v[4:5], v[0:1], 2, s[2:3]
	global_store_dword v[4:5], v6, off
	s_mov_b32 s2, -2
	s_mov_b64 s[28:29], 0
	v_mov_b64_e32 v[6:7], v[8:9]
	v_mov_b32_e32 v16, 0
	v_readlane_b32 s57, v253, 33
	v_readlane_b32 s60, v253, 36
	v_readlane_b32 s61, v253, 37
	v_readlane_b32 s62, v253, 38
	v_readlane_b32 s63, v253, 39
	v_readlane_b32 s64, v253, 40
	v_readlane_b32 s65, v253, 41
	v_readlane_b32 s66, v253, 42
	v_readlane_b32 s67, v253, 43
	v_readlane_b32 s68, v253, 44
	v_readlane_b32 s69, v253, 45
	v_readlane_b32 s70, v253, 46
	v_readlane_b32 s71, v253, 47
	v_mov_b32_e32 v45, 0
	s_mov_b32 s2, 0
MXABS_0:
	global_load_dwordx4 v[28:31], v[6:7], off
	global_load_dwordx4 v[32:35], v[6:7], off offset:16
	global_load_dwordx4 v[36:39], v[6:7], off offset:32
	global_load_dwordx4 v[40:43], v[6:7], off offset:48
	s_add_i32 s2, s2, 16
	s_cmp_eq_u32 s2, 128
	s_waitcnt vmcnt(0)
	v_lshl_add_u64 v[6:7], v[6:7], 0, 64
	v_max_f32_e64 v44, |v28|, |v28|
	v_max_f32_e32 v45, v45, v44
	v_max_f32_e64 v44, |v29|, |v29|
	v_max_f32_e32 v45, v45, v44
	v_max_f32_e64 v44, |v30|, |v30|
	v_max_f32_e32 v45, v45, v44
	v_max_f32_e64 v44, |v31|, |v31|
	v_max_f32_e32 v45, v45, v44
	v_max_f32_e64 v44, |v32|, |v32|
	v_max_f32_e32 v45, v45, v44
	v_max_f32_e64 v44, |v33|, |v33|
	v_max_f32_e32 v45, v45, v44
	v_max_f32_e64 v44, |v34|, |v34|
	v_max_f32_e32 v45, v45, v44
	v_max_f32_e64 v44, |v35|, |v35|
	v_max_f32_e32 v45, v45, v44
	v_max_f32_e64 v44, |v36|, |v36|
	v_max_f32_e32 v45, v45, v44
	v_max_f32_e64 v44, |v37|, |v37|
	v_max_f32_e32 v45, v45, v44
	v_max_f32_e64 v44, |v38|, |v38|
	v_max_f32_e32 v45, v45, v44
	v_max_f32_e64 v44, |v39|, |v39|
	v_max_f32_e32 v45, v45, v44
	v_max_f32_e64 v44, |v40|, |v40|
	v_max_f32_e32 v45, v45, v44
	v_max_f32_e64 v44, |v41|, |v41|
	v_max_f32_e32 v45, v45, v44
	v_max_f32_e64 v44, |v42|, |v42|
	v_max_f32_e32 v45, v45, v44
	v_max_f32_e64 v44, |v43|, |v43|
	v_max_f32_e32 v45, v45, v44
	s_cbranch_scc0 MXABS_0
	v_mov_b32_e32 v6, v45
	v_readlane_b32 s56, v253, 32
	v_readlane_b32 s60, v253, 36
	v_readlane_b32 s61, v253, 37
	v_mov_b32_e32 v16, 0
	s_mov_b32 s2, -2
	v_lshl_add_u64 v[8:9], v[10:11], 2, s[60:61]
	s_mov_b64 s[26:27], 0
	s_mov_b64 s[28:29], 0
	v_mov_b64_e32 v[14:15], v[8:9]
	v_mov_b32_e32 v17, 0
	v_readlane_b32 s57, v253, 33
	v_readlane_b32 s58, v253, 34
	v_readlane_b32 s59, v253, 35
	v_readlane_b32 s62, v253, 38
	v_readlane_b32 s63, v253, 39
	v_readlane_b32 s64, v253, 40
	v_readlane_b32 s65, v253, 41
	v_readlane_b32 s66, v253, 42
	v_readlane_b32 s67, v253, 43
	v_readlane_b32 s68, v253, 44
	v_readlane_b32 s69, v253, 45
	v_readlane_b32 s70, v253, 46
	v_readlane_b32 s71, v253, 47
	v_mov_b32_e32 v45, 0
	s_mov_b32 s2, 0
; __device__ __forceinline__ float absmax_n(const float* w, int n) { float m = 0.f; for (int i = 0; i < n; ++i) m = fmaxf(m, fabsf(w[i])); return m; }
; __global__ void __launch_bounds__(512, 2) mega_fwd(Args args) {
;     ...
;                 const float mAq = absmax_n(args.in[9] + l * 128, 128), mAk = absmax_n(args.in[10] + l * 128, 128);
;                 const float mBqn = absmax_n(args.in[11] + l * 128, 128), mBqr = absmax_n(args.in[12] + l * 64, 64), mBkn = absmax_n(args.in[16] + l * 128, 128), mBkr = absmax_n(args.in[17] + l * 64, 64);
MXABS_1:
	global_load_dwordx4 v[28:31], v[14:15], off
	global_load_dwordx4 v[32:35], v[14:15], off offset:16
	global_load_dwordx4 v[36:39], v[14:15], off offset:32
	global_load_dwordx4 v[40:43], v[14:15], off offset:48
	s_add_i32 s2, s2, 16
	s_cmp_eq_u32 s2, 128
	s_waitcnt vmcnt(0)
	v_lshl_add_u64 v[14:15], v[14:15], 0, 64
	v_max_f32_e64 v44, |v28|, |v28|
	v_max_f32_e32 v45, v45, v44
	v_max_f32_e64 v44, |v29|, |v29|
	v_max_f32_e32 v45, v45, v44
	v_max_f32_e64 v44, |v30|, |v30|
	v_max_f32_e32 v45, v45, v44
	v_max_f32_e64 v44, |v31|, |v31|
	v_max_f32_e32 v45, v45, v44
	v_max_f32_e64 v44, |v32|, |v32|
	v_max_f32_e32 v45, v45, v44
	v_max_f32_e64 v44, |v33|, |v33|
	v_max_f32_e32 v45, v45, v44
	v_max_f32_e64 v44, |v34|, |v34|
	v_max_f32_e32 v45, v45, v44
	v_max_f32_e64 v44, |v35|, |v35|
	v_max_f32_e32 v45, v45, v44
	v_max_f32_e64 v44, |v36|, |v36|
	v_max_f32_e32 v45, v45, v44
	v_max_f32_e64 v44, |v37|, |v37|
	v_max_f32_e32 v45, v45, v44
	v_max_f32_e64 v44, |v38|, |v38|
	v_max_f32_e32 v45, v45, v44
	v_max_f32_e64 v44, |v39|, |v39|
	v_max_f32_e32 v45, v45, v44
	v_max_f32_e64 v44, |v40|, |v40|
	v_max_f32_e32 v45, v45, v44
	v_max_f32_e64 v44, |v41|, |v41|
	v_max_f32_e32 v45, v45, v44
	v_max_f32_e64 v44, |v42|, |v42|
	v_max_f32_e32 v45, v45, v44
	v_max_f32_e64 v44, |v43|, |v43|
	v_max_f32_e32 v45, v45, v44
	s_cbranch_scc0 MXABS_1
	v_mov_b32_e32 v1, v45
	v_readlane_b32 s56, v253, 32
	v_readlane_b32 s62, v253, 38
	v_readlane_b32 s63, v253, 39
	v_mov_b32_e32 v17, 0
	s_mov_b32 s2, -2
	v_lshl_add_u64 v[12:13], v[10:11], 2, s[62:63]
	s_mov_b64 s[26:27], 0
	s_mov_b64 s[28:29], 0
	v_mov_b64_e32 v[8:9], v[12:13]
	v_mov_b32_e32 v18, 0
	v_readlane_b32 s57, v253, 33
	v_readlane_b32 s58, v253, 34
	v_readlane_b32 s59, v253, 35
	v_readlane_b32 s60, v253, 36
	v_readlane_b32 s61, v253, 37
	v_readlane_b32 s64, v253, 40
	v_readlane_b32 s65, v253, 41
	v_readlane_b32 s66, v253, 42
	v_readlane_b32 s67, v253, 43
	v_readlane_b32 s68, v253, 44
	v_readlane_b32 s69, v253, 45
	v_readlane_b32 s70, v253, 46
	v_readlane_b32 s71, v253, 47
	v_mov_b32_e32 v45, 0
	s_mov_b32 s2, 0
MXABS_2:
	global_load_dwordx4 v[28:31], v[8:9], off
	global_load_dwordx4 v[32:35], v[8:9], off offset:16
	global_load_dwordx4 v[36:39], v[8:9], off offset:32
	global_load_dwordx4 v[40:43], v[8:9], off offset:48
	s_add_i32 s2, s2, 16
	s_cmp_eq_u32 s2, 128
	s_waitcnt vmcnt(0)
	v_lshl_add_u64 v[8:9], v[8:9], 0, 64
	v_max_f32_e64 v44, |v28|, |v28|
	v_max_f32_e32 v45, v45, v44
	v_max_f32_e64 v44, |v29|, |v29|
	v_max_f32_e32 v45, v45, v44
	v_max_f32_e64 v44, |v30|, |v30|
	v_max_f32_e32 v45, v45, v44
	v_max_f32_e64 v44, |v31|, |v31|
	v_max_f32_e32 v45, v45, v44
	v_max_f32_e64 v44, |v32|, |v32|
	v_max_f32_e32 v45, v45, v44
	v_max_f32_e64 v44, |v33|, |v33|
	v_max_f32_e32 v45, v45, v44
	v_max_f32_e64 v44, |v34|, |v34|
	v_max_f32_e32 v45, v45, v44
	v_max_f32_e64 v44, |v35|, |v35|
	v_max_f32_e32 v45, v45, v44
	v_max_f32_e64 v44, |v36|, |v36|
	v_max_f32_e32 v45, v45, v44
	v_max_f32_e64 v44, |v37|, |v37|
	v_max_f32_e32 v45, v45, v44
	v_max_f32_e64 v44, |v38|, |v38|
	v_max_f32_e32 v45, v45, v44
	v_max_f32_e64 v44, |v39|, |v39|
	v_max_f32_e32 v45, v45, v44
	v_max_f32_e64 v44, |v40|, |v40|
	v_max_f32_e32 v45, v45, v44
	v_max_f32_e64 v44, |v41|, |v41|
	v_max_f32_e32 v45, v45, v44
	v_max_f32_e64 v44, |v42|, |v42|
	v_max_f32_e32 v45, v45, v44
	v_max_f32_e64 v44, |v43|, |v43|
	v_max_f32_e32 v45, v45, v44
	s_cbranch_scc0 MXABS_2
	v_mov_b32_e32 v8, v45
	v_readlane_b32 s56, v253, 32
	v_readlane_b32 s64, v253, 40
	v_readlane_b32 s65, v253, 41
	v_mov_b32_e32 v18, 0
	s_mov_b32 s2, -2
	v_lshl_add_u64 v[12:13], v[2:3], 2, s[64:65]
	s_mov_b64 s[26:27], 0
	s_mov_b64 s[28:29], 0
	v_mov_b64_e32 v[16:17], v[12:13]
	v_mov_b32_e32 v19, 0
	v_readlane_b32 s57, v253, 33
	v_readlane_b32 s58, v253, 34
	v_readlane_b32 s59, v253, 35
	v_readlane_b32 s60, v253, 36
	v_readlane_b32 s61, v253, 37
	v_readlane_b32 s62, v253, 38
	v_readlane_b32 s63, v253, 39
	v_readlane_b32 s66, v253, 42
	v_readlane_b32 s67, v253, 43
	v_readlane_b32 s68, v253, 44
	v_readlane_b32 s69, v253, 45
	v_readlane_b32 s70, v253, 46
	v_readlane_b32 s71, v253, 47
	v_mov_b32_e32 v45, 0
	s_mov_b32 s2, 0
MXABS_3:
	global_load_dwordx4 v[28:31], v[16:17], off
	global_load_dwordx4 v[32:35], v[16:17], off offset:16
	global_load_dwordx4 v[36:39], v[16:17], off offset:32
	global_load_dwordx4 v[40:43], v[16:17], off offset:48
	s_add_i32 s2, s2, 16
	s_cmp_eq_u32 s2, 64
	s_waitcnt vmcnt(0)
	v_lshl_add_u64 v[16:17], v[16:17], 0, 64
	v_max_f32_e64 v44, |v28|, |v28|
	v_max_f32_e32 v45, v45, v44
	v_max_f32_e64 v44, |v29|, |v29|
	v_max_f32_e32 v45, v45, v44
	v_max_f32_e64 v44, |v30|, |v30|
	v_max_f32_e32 v45, v45, v44
	v_max_f32_e64 v44, |v31|, |v31|
	v_max_f32_e32 v45, v45, v44
	v_max_f32_e64 v44, |v32|, |v32|
	v_max_f32_e32 v45, v45, v44
	v_max_f32_e64 v44, |v33|, |v33|
	v_max_f32_e32 v45, v45, v44
	v_max_f32_e64 v44, |v34|, |v34|
	v_max_f32_e32 v45, v45, v44
	v_max_f32_e64 v44, |v35|, |v35|
	v_max_f32_e32 v45, v45, v44
	v_max_f32_e64 v44, |v36|, |v36|
	v_max_f32_e32 v45, v45, v44
	v_max_f32_e64 v44, |v37|, |v37|
	v_max_f32_e32 v45, v45, v44
	v_max_f32_e64 v44, |v38|, |v38|
	v_max_f32_e32 v45, v45, v44
	v_max_f32_e64 v44, |v39|, |v39|
	v_max_f32_e32 v45, v45, v44
	v_max_f32_e64 v44, |v40|, |v40|
	v_max_f32_e32 v45, v45, v44
	v_max_f32_e64 v44, |v41|, |v41|
	v_max_f32_e32 v45, v45, v44
	v_max_f32_e64 v44, |v42|, |v42|
	v_max_f32_e32 v45, v45, v44
	v_max_f32_e64 v44, |v43|, |v43|
	v_max_f32_e32 v45, v45, v44
	s_cbranch_scc0 MXABS_3
	v_mov_b32_e32 v9, v45
	v_readlane_b32 s44, v254, 13
	v_readlane_b32 s45, v254, 14
	v_mov_b32_e32 v17, 0
	s_mov_b32 s2, -2
	v_lshl_add_u64 v[12:13], v[10:11], 2, s[44:45]
	s_mov_b64 s[26:27], 0
	s_mov_b64 s[28:29], 0
	v_mov_b64_e32 v[10:11], v[12:13]
	v_mov_b32_e32 v18, 0
	v_readlane_b32 s46, v254, 15
	v_readlane_b32 s47, v254, 16
	v_readlane_b32 s48, v254, 17
	v_readlane_b32 s49, v254, 18
	v_readlane_b32 s50, v254, 19
	v_readlane_b32 s51, v254, 20
	v_readlane_b32 s52, v254, 21
	v_readlane_b32 s53, v254, 22
	v_readlane_b32 s54, v254, 23
	v_readlane_b32 s55, v254, 24
	v_readlane_b32 s56, v254, 25
	v_readlane_b32 s57, v254, 26
	v_readlane_b32 s58, v254, 27
	v_readlane_b32 s59, v254, 28
	v_mov_b32_e32 v45, 0
	s_mov_b32 s2, 0
; __device__ __forceinline__ float absmax_n(const float* w, int n) { float m = 0.f; for (int i = 0; i < n; ++i) m = fmaxf(m, fabsf(w[i])); return m; }
; __global__ void __launch_bounds__(512, 2) mega_fwd(Args args) {
;     ...
;                 const float mBqn = absmax_n(args.in[11] + l * 128, 128), mBqr = absmax_n(args.in[12] + l * 64, 64), mBkn = absmax_n(args.in[16] + l * 128, 128), mBkr = absmax_n(args.in[17] + l * 64, 64);
MXABS_4:
	global_load_dwordx4 v[28:31], v[10:11], off
	global_load_dwordx4 v[32:35], v[10:11], off offset:16
	global_load_dwordx4 v[36:39], v[10:11], off offset:32
	global_load_dwordx4 v[40:43], v[10:11], off offset:48
	s_add_i32 s2, s2, 16
	s_cmp_eq_u32 s2, 128
	s_waitcnt vmcnt(0)
	v_lshl_add_u64 v[10:11], v[10:11], 0, 64
	v_max_f32_e64 v44, |v28|, |v28|
	v_max_f32_e32 v45, v45, v44
	v_max_f32_e64 v44, |v29|, |v29|
	v_max_f32_e32 v45, v45, v44
	v_max_f32_e64 v44, |v30|, |v30|
	v_max_f32_e32 v45, v45, v44
	v_max_f32_e64 v44, |v31|, |v31|
	v_max_f32_e32 v45, v45, v44
	v_max_f32_e64 v44, |v32|, |v32|
	v_max_f32_e32 v45, v45, v44
	v_max_f32_e64 v44, |v33|, |v33|
	v_max_f32_e32 v45, v45, v44
	v_max_f32_e64 v44, |v34|, |v34|
	v_max_f32_e32 v45, v45, v44
	v_max_f32_e64 v44, |v35|, |v35|
	v_max_f32_e32 v45, v45, v44
	v_max_f32_e64 v44, |v36|, |v36|
	v_max_f32_e32 v45, v45, v44
	v_max_f32_e64 v44, |v37|, |v37|
	v_max_f32_e32 v45, v45, v44
	v_max_f32_e64 v44, |v38|, |v38|
	v_max_f32_e32 v45, v45, v44
	v_max_f32_e64 v44, |v39|, |v39|
	v_max_f32_e32 v45, v45, v44
	v_max_f32_e64 v44, |v40|, |v40|
	v_max_f32_e32 v45, v45, v44
	v_max_f32_e64 v44, |v41|, |v41|
	v_max_f32_e32 v45, v45, v44
	v_max_f32_e64 v44, |v42|, |v42|
	v_max_f32_e32 v45, v45, v44
	v_max_f32_e64 v44, |v43|, |v43|
	v_max_f32_e32 v45, v45, v44
	s_cbranch_scc0 MXABS_4
	v_mov_b32_e32 v10, v45
	v_readlane_b32 s44, v254, 13
	v_readlane_b32 s46, v254, 15
	v_readlane_b32 s47, v254, 16
	v_mov_b32_e32 v18, 0
	s_mov_b32 s2, -2
	v_lshl_add_u64 v[12:13], v[2:3], 2, s[46:47]
	s_mov_b64 s[26:27], 0
	s_mov_b64 s[28:29], 0
	v_mov_b64_e32 v[16:17], v[12:13]
	v_mov_b32_e32 v19, 0
	v_readlane_b32 s45, v254, 14
	v_readlane_b32 s48, v254, 17
	v_readlane_b32 s49, v254, 18
	v_readlane_b32 s50, v254, 19
	v_readlane_b32 s51, v254, 20
	v_readlane_b32 s52, v254, 21
	v_readlane_b32 s53, v254, 22
	v_readlane_b32 s54, v254, 23
	v_readlane_b32 s55, v254, 24
	v_readlane_b32 s56, v254, 25
	v_readlane_b32 s57, v254, 26
	v_readlane_b32 s58, v254, 27
	v_readlane_b32 s59, v254, 28
	v_mov_b32_e32 v45, 0
	s_mov_b32 s2, 0
MXABS_5:
	global_load_dwordx4 v[28:31], v[16:17], off
	global_load_dwordx4 v[32:35], v[16:17], off offset:16
	global_load_dwordx4 v[36:39], v[16:17], off offset:32
	global_load_dwordx4 v[40:43], v[16:17], off offset:48
	s_add_i32 s2, s2, 16
	s_cmp_eq_u32 s2, 64
	s_waitcnt vmcnt(0)
	v_lshl_add_u64 v[16:17], v[16:17], 0, 64
	v_max_f32_e64 v44, |v28|, |v28|
	v_max_f32_e32 v45, v45, v44
	v_max_f32_e64 v44, |v29|, |v29|
	v_max_f32_e32 v45, v45, v44
	v_max_f32_e64 v44, |v30|, |v30|
	v_max_f32_e32 v45, v45, v44
	v_max_f32_e64 v44, |v31|, |v31|
	v_max_f32_e32 v45, v45, v44
	v_max_f32_e64 v44, |v32|, |v32|
	v_max_f32_e32 v45, v45, v44
	v_max_f32_e64 v44, |v33|, |v33|
	v_max_f32_e32 v45, v45, v44
	v_max_f32_e64 v44, |v34|, |v34|
	v_max_f32_e32 v45, v45, v44
	v_max_f32_e64 v44, |v35|, |v35|
	v_max_f32_e32 v45, v45, v44
	v_max_f32_e64 v44, |v36|, |v36|
	v_max_f32_e32 v45, v45, v44
	v_max_f32_e64 v44, |v37|, |v37|
	v_max_f32_e32 v45, v45, v44
	v_max_f32_e64 v44, |v38|, |v38|
	v_max_f32_e32 v45, v45, v44
	v_max_f32_e64 v44, |v39|, |v39|
	v_max_f32_e32 v45, v45, v44
	v_max_f32_e64 v44, |v40|, |v40|
	v_max_f32_e32 v45, v45, v44
	v_max_f32_e64 v44, |v41|, |v41|
	v_max_f32_e32 v45, v45, v44
	v_max_f32_e64 v44, |v42|, |v42|
	v_max_f32_e32 v45, v45, v44
	v_max_f32_e64 v44, |v43|, |v43|
	v_max_f32_e32 v45, v45, v44
	s_cbranch_scc0 MXABS_5
	v_mov_b32_e32 v11, v45
	v_readlane_b32 s44, v254, 13
	v_readlane_b32 s48, v254, 17
	v_readlane_b32 s49, v254, 18
	v_mov_b32_e32 v19, 0
	s_mov_b32 s2, -2
	v_lshl_add_u64 v[12:13], v[2:3], 2, s[48:49]
	s_mov_b64 s[26:27], 0
	s_mov_b64 s[28:29], 0
	v_mov_b64_e32 v[16:17], v[12:13]
	v_mov_b32_e32 v20, 0
	v_readlane_b32 s45, v254, 14
	v_readlane_b32 s46, v254, 15
	v_readlane_b32 s47, v254, 16
	v_readlane_b32 s50, v254, 19
	v_readlane_b32 s51, v254, 20
	v_readlane_b32 s52, v254, 21
	v_readlane_b32 s53, v254, 22
	v_readlane_b32 s54, v254, 23
	v_readlane_b32 s55, v254, 24
	v_readlane_b32 s56, v254, 25
	v_readlane_b32 s57, v254, 26
	v_readlane_b32 s58, v254, 27
	v_readlane_b32 s59, v254, 28
	v_mov_b32_e32 v45, 0
	s_mov_b32 s2, 0
; __device__ __forceinline__ float absmax_n(const float* w, int n) { float m = 0.f; for (int i = 0; i < n; ++i) m = fmaxf(m, fabsf(w[i])); return m; }
; __global__ void __launch_bounds__(512, 2) mega_fwd(Args args) {
;     ...
;                 const float mCq = absmax_n(args.in[18] + l * 64, 64), mCk = absmax_n(args.in[19] + l * 64, 64);
;                 const float L2E = 1.4426950408889634f;
;                 LAM[l * 4 + 1] = -(sqrtf(128.f) * mAq * mAk) * L2E;
;                 LAM[l * 4 + 2] = -(sqrtf(128.f * mBqn * mBqn + 64.f * mBqr * mBqr) * sqrtf(128.f * mBkn * mBkn + 64.f * mBkr * mBkr) * 0.07216878364870323f) * L2E;
;                 LAM[l * 4 + 3] = -(8.f * mCq * mCk) * L2E;
MXABS_6:
	global_load_dwordx4 v[28:31], v[16:17], off
	global_load_dwordx4 v[32:35], v[16:17], off offset:16
	global_load_dwordx4 v[36:39], v[16:17], off offset:32
	global_load_dwordx4 v[40:43], v[16:17], off offset:48
	s_add_i32 s2, s2, 16
	s_cmp_eq_u32 s2, 64
	s_waitcnt vmcnt(0)
	v_lshl_add_u64 v[16:17], v[16:17], 0, 64
	v_max_f32_e64 v44, |v28|, |v28|
	v_max_f32_e32 v45, v45, v44
	v_max_f32_e64 v44, |v29|, |v29|
	v_max_f32_e32 v45, v45, v44
	v_max_f32_e64 v44, |v30|, |v30|
	v_max_f32_e32 v45, v45, v44
	v_max_f32_e64 v44, |v31|, |v31|
	v_max_f32_e32 v45, v45, v44
	v_max_f32_e64 v44, |v32|, |v32|
	v_max_f32_e32 v45, v45, v44
	v_max_f32_e64 v44, |v33|, |v33|
	v_max_f32_e32 v45, v45, v44
	v_max_f32_e64 v44, |v34|, |v34|
	v_max_f32_e32 v45, v45, v44
	v_max_f32_e64 v44, |v35|, |v35|
	v_max_f32_e32 v45, v45, v44
	v_max_f32_e64 v44, |v36|, |v36|
	v_max_f32_e32 v45, v45, v44
	v_max_f32_e64 v44, |v37|, |v37|
	v_max_f32_e32 v45, v45, v44
	v_max_f32_e64 v44, |v38|, |v38|
	v_max_f32_e32 v45, v45, v44
	v_max_f32_e64 v44, |v39|, |v39|
	v_max_f32_e32 v45, v45, v44
	v_max_f32_e64 v44, |v40|, |v40|
	v_max_f32_e32 v45, v45, v44
	v_max_f32_e64 v44, |v41|, |v41|
	v_max_f32_e32 v45, v45, v44
	v_max_f32_e64 v44, |v42|, |v42|
	v_max_f32_e32 v45, v45, v44
	v_max_f32_e64 v44, |v43|, |v43|
	v_max_f32_e32 v45, v45, v44
	s_cbranch_scc0 MXABS_6
	v_mov_b32_e32 v16, v45
	v_readlane_b32 s44, v254, 13
	v_readlane_b32 s50, v254, 19
	v_readlane_b32 s51, v254, 20
	v_mov_b32_e32 v18, 0
	s_mov_b32 s2, -2
	v_lshl_add_u64 v[2:3], v[2:3], 2, s[50:51]
	s_mov_b64 s[26:27], 0
	s_mov_b64 s[28:29], 0
	v_mov_b64_e32 v[14:15], v[2:3]
	v_mov_b32_e32 v19, 0
	v_readlane_b32 s45, v254, 14
	v_readlane_b32 s46, v254, 15
	v_readlane_b32 s47, v254, 16
	v_readlane_b32 s48, v254, 17
	v_readlane_b32 s49, v254, 18
	v_readlane_b32 s52, v254, 21
	v_readlane_b32 s53, v254, 22
	v_readlane_b32 s54, v254, 23
	v_readlane_b32 s55, v254, 24
	v_readlane_b32 s56, v254, 25
	v_readlane_b32 s57, v254, 26
	v_readlane_b32 s58, v254, 27
	v_readlane_b32 s59, v254, 28
	v_mov_b32_e32 v45, 0
	s_mov_b32 s2, 0
MXABS_7:
	global_load_dwordx4 v[28:31], v[14:15], off
	global_load_dwordx4 v[32:35], v[14:15], off offset:16
	global_load_dwordx4 v[36:39], v[14:15], off offset:32
	global_load_dwordx4 v[40:43], v[14:15], off offset:48
	s_add_i32 s2, s2, 16
	s_cmp_eq_u32 s2, 64
	s_waitcnt vmcnt(0)
	v_lshl_add_u64 v[14:15], v[14:15], 0, 64
	v_max_f32_e64 v44, |v28|, |v28|
	v_max_f32_e32 v45, v45, v44
	v_max_f32_e64 v44, |v29|, |v29|
	v_max_f32_e32 v45, v45, v44
	v_max_f32_e64 v44, |v30|, |v30|
	v_max_f32_e32 v45, v45, v44
	v_max_f32_e64 v44, |v31|, |v31|
	v_max_f32_e32 v45, v45, v44
	v_max_f32_e64 v44, |v32|, |v32|
	v_max_f32_e32 v45, v45, v44
	v_max_f32_e64 v44, |v33|, |v33|
	v_max_f32_e32 v45, v45, v44
	v_max_f32_e64 v44, |v34|, |v34|
	v_max_f32_e32 v45, v45, v44
	v_max_f32_e64 v44, |v35|, |v35|
	v_max_f32_e32 v45, v45, v44
	v_max_f32_e64 v44, |v36|, |v36|
	v_max_f32_e32 v45, v45, v44
	v_max_f32_e64 v44, |v37|, |v37|
	v_max_f32_e32 v45, v45, v44
	v_max_f32_e64 v44, |v38|, |v38|
	v_max_f32_e32 v45, v45, v44
	v_max_f32_e64 v44, |v39|, |v39|
	v_max_f32_e32 v45, v45, v44
	v_max_f32_e64 v44, |v40|, |v40|
	v_max_f32_e32 v45, v45, v44
	v_max_f32_e64 v44, |v41|, |v41|
	v_max_f32_e32 v45, v45, v44
	v_max_f32_e64 v44, |v42|, |v42|
	v_max_f32_e32 v45, v45, v44
	v_max_f32_e64 v44, |v43|, |v43|
	v_max_f32_e32 v45, v45, v44
	s_cbranch_scc0 MXABS_7
	v_mov_b32_e32 v14, v45
	s_mov_b32 s2, 0x43000000
	s_mov_b32 s3, 0x42800000
	v_pk_mul_f32 v[2:3], v[8:9], s[2:3]
	s_mov_b32 s4, 0xf800000
	v_pk_mul_f32 v[2:3], v[8:9], v[2:3]
	v_xor_b32_e32 v182, 0x80000000, v1
	v_add_f32_e32 v2, v2, v3
	v_mul_f32_e32 v3, 0x4f800000, v2
	v_cmp_gt_f32_e32 vcc, s4, v2
	s_nop 1
	v_cndmask_b32_e32 v7, v2, v3, vcc
	v_sqrt_f32_e32 v2, v7
	s_nop 0
	v_add_u32_e32 v1, -1, v2
	v_fma_f32 v3, -v1, v2, v7
	v_cmp_ge_f32_e64 s[44:45], 0, v3
	v_add_u32_e32 v3, 1, v2
	s_nop 0
	v_cndmask_b32_e64 v1, v2, v1, s[44:45]
	v_fma_f32 v2, -v3, v2, v7
	v_cmp_lt_f32_e64 s[44:45], 0, v2
	s_nop 1
	v_cndmask_b32_e64 v1, v1, v3, s[44:45]
	v_pk_mul_f32 v[2:3], v[10:11], s[2:3]
	v_mul_f32_e32 v8, 0x37800000, v1
	v_pk_mul_f32 v[2:3], v[10:11], v[2:3]
	v_cndmask_b32_e32 v1, v1, v8, vcc
	v_add_f32_e32 v2, v2, v3
	v_mul_f32_e32 v3, 0x4f800000, v2
	v_cmp_gt_f32_e64 s[44:45], s4, v2
	v_cmp_class_f32_e32 vcc, v7, v232
	s_mov_b32 s2, 0x3fb8aa3b
	v_cndmask_b32_e64 v2, v2, v3, s[44:45]
	v_sqrt_f32_e32 v3, v2
	v_cndmask_b32_e32 v7, v1, v7, vcc
	v_add_u32_e32 v1, -1, v3
	v_fma_f32 v8, -v1, v3, v2
	v_cmp_ge_f32_e32 vcc, 0, v8
	v_add_u32_e32 v8, 1, v3
	s_nop 0
	v_cndmask_b32_e32 v1, v3, v1, vcc
	v_fma_f32 v3, -v8, v3, v2
	v_cmp_lt_f32_e32 vcc, 0, v3
	s_nop 1
	v_cndmask_b32_e32 v1, v1, v8, vcc
	v_mul_f32_e32 v3, 0x37800000, v1
	v_cndmask_b32_e64 v1, v1, v3, s[44:45]
	v_cmp_class_f32_e32 vcc, v2, v232
	s_nop 1
	v_cndmask_b32_e32 v181, v1, v2, vcc
	v_pk_mul_f32 v[2:3], v[6:7], v[180:181]
	v_mul_f32_e32 v1, 0xc1000000, v16
	v_pk_mul_f32 v[2:3], v[2:3], v[182:183]
	v_mul_f32_e32 v1, v1, v14
	v_pk_mul_f32 v[6:7], v[2:3], s[2:3] op_sel_hi:[1,0]
	v_mul_f32_e32 v8, 0x3fb8aa3b, v1
	global_store_dwordx3 v[4:5], v[6:8], off offset:4
